# GQA main loop: K-prefetch row index as a loop-carried counter (10 SALU less per two key tiles)
# baseline (speedup 1.0000x reference)
.LBB0_706:
	s_mul_hi_i32 s0, s14, 0x2aaaaaab
	s_lshr_b32 s1, s0, 31
	s_ashr_i32 s0, s0, 5
	s_add_i32 s0, s0, s1
	s_mul_i32 s1, s0, 0xc0
	s_sub_i32 s1, s14, s1
	s_and_b32 s2, s1, 3
	s_bfe_u32 s4, s1, 0x10002
	s_mul_i32 s2, s2, 24
	s_ashr_i32 s1, s1, 3
	s_add_i32 s5, s2, s1
	s_bfe_i32 s2, s5, 0x80000
	s_bfe_u32 s2, s2, 0x5000a
	s_add_i32 s2, s5, s2
	s_bfe_i32 s2, s2, 0x80000
	s_mul_i32 s1, s4, 3
	s_bfe_u32 s2, s2, 0x80005
	s_add_i32 s6, s1, s2
	s_ashr_i32 s1, s0, 31
	s_lshl_b64 s[2:3], s[0:1], 13
	s_lshl_b32 s1, s5, 8
	s_and_b32 s1, s1, 0x1f00
	s_or_b32 s2, s2, s1
	s_mul_hi_u32 s5, s2, 0xe00
	s_mul_i32 s7, s3, 0xe00
	s_mul_i32 s1, s2, 0xe00
	s_add_i32 s5, s5, s7
	v_readlane_b32 s8, v254, 35
	v_readlane_b32 s9, v254, 36
	s_add_u32 s1, s8, s1
	s_addc_u32 s5, s9, s5
	s_lshl_b32 s16, s6, 6
	s_lshl_b32 s6, s6, 7
	s_add_u32 s1, s1, s6
	s_addc_u32 s5, s5, 0
	s_lshl_b32 s4, s4, 7
	s_add_u32 s6, s10, s4
	s_addc_u32 s7, s11, 0
	v_mov_b32_e32 v42, v191
	s_add_u32 s18, s12, s4
	s_addc_u32 s19, s13, 0
	v_readfirstlane_b32 s17, v42
	s_ashr_i32 s15, s17, 6
	s_lshl_b32 s8, s0, 8
	s_lshl_b32 s36, s15, 5
	s_lshl_b32 s9, s0, 13
	s_add_i32 s20, s8, 0x4000
	v_and_b32_e32 v189, 63, v42
	s_ashr_i32 s37, s36, 31
	s_mul_i32 s0, s15, 0x1c000
	s_mul_hi_i32 s4, s36, 0xe00
	s_add_u32 s22, s1, s0
	v_mul_u32_u24_e32 v0, 0x700, v189
	s_addc_u32 s23, s5, s4
	v_lshlrev_b32_e32 v0, 1, v0
	s_lshl_b32 s0, s15, 3
	v_lshl_add_u64 v[2:3], s[6:7], 0, v[0:1]
	s_ashr_i32 s1, s0, 31
	v_lshl_add_u64 v[192:193], s[0:1], 1, v[2:3]
	s_lshl_b32 s0, s15, 4
	v_bfe_u32 v0, v42, 2, 4
	v_and_or_b32 v0, s0, 48, v0
	v_mul_u32_u24_e32 v0, 0x700, v0
	s_ashr_i32 s0, s17, 3
	v_lshlrev_b32_e32 v0, 1, v0
	s_andn2_b32 s0, s0, 31
	v_lshl_add_u64 v[2:3], s[18:19], 0, v[0:1]
	s_ashr_i32 s1, s0, 31
	v_lshlrev_b32_e32 v198, 3, v42
	s_and_b32 s4, s17, 0x3fffffc0
	v_lshl_add_u64 v[2:3], s[0:1], 1, v[2:3]
	v_and_b32_e32 v201, 24, v198
	s_lshl_b32 s0, s15, 10
	v_lshlrev_b32_e32 v0, 1, v201
	s_cmp_lg_u32 0, -1
	v_lshl_add_u64 v[194:195], v[2:3], 0, v[0:1]
	s_cselect_b32 s1, 0, 0
	v_and_b32_e32 v199, 31, v42
	v_bfe_u32 v200, v42, 5, 1
	s_add_i32 s18, s0, s1
	v_mad_i64_i32 v[2:3], s[0:1], s9, v217, v[192:193]
	s_mov_b32 m0, s18
	s_nop 0
	global_load_lds_dwordx4 v[2:3], off
	s_add_i32 s19, s18, 0x6000
	v_mad_i64_i32 v[82:83], s[0:1], s9, v217, v[194:195]
	s_mov_b32 m0, s19
	s_nop 0
	global_load_lds_dwordx4 v[82:83], off
	s_or_b32 s1, s9, 64
	v_mul_u32_u24_e32 v0, 0x700, v199
	v_lshlrev_b32_e32 v203, 4, v200
	v_mad_i64_i32 v[2:3], s[6:7], s1, v217, v[192:193]
	s_add_i32 s0, s18, 0x2000
	s_mov_b32 m0, s0
	s_nop 0
	global_load_lds_dwordx4 v[2:3], off
	v_lshl_or_b32 v0, v0, 1, v203
	global_load_dwordx4 v[142:145], v0, s[22:23]
	global_load_dwordx4 v[138:141], v0, s[22:23] offset:32
	global_load_dwordx4 v[130:133], v0, s[22:23] offset:64
	global_load_dwordx4 v[122:125], v0, s[22:23] offset:96
	v_lshlrev_b32_e32 v2, 10, v200
	v_lshlrev_b32_e32 v3, 4, v199
	v_add3_u32 v206, 0, v2, v3
	v_mov_b32_e32 v2, v1
	v_mov_b32_e32 v3, v1
	v_mov_b32_e32 v4, v1
	v_mov_b32_e32 v5, v1
	v_mov_b32_e32 v6, v1
	v_mov_b32_e32 v7, v1
	v_mov_b32_e32 v8, v1
	v_mov_b32_e32 v9, v1
	v_mov_b32_e32 v10, v1
	v_mov_b32_e32 v11, v1
	v_mov_b32_e32 v12, v1
	v_mov_b32_e32 v13, v1
	v_mov_b32_e32 v14, v1
	v_mov_b32_e32 v15, v1
	v_mov_b32_e32 v0, v1
	v_mov_b64_e32 v[16:17], v[14:15]
	v_mov_b64_e32 v[14:15], v[12:13]
	v_mov_b64_e32 v[12:13], v[10:11]
	v_mov_b64_e32 v[10:11], v[8:9]
	v_mov_b64_e32 v[8:9], v[6:7]
	v_mov_b64_e32 v[6:7], v[4:5]
	v_mov_b64_e32 v[4:5], v[2:3]
	v_mov_b64_e32 v[2:3], v[0:1]
	s_or_b32 s0, s9, 0x80
	v_mad_i64_i32 v[18:19], s[6:7], s0, v217, v[192:193]
	s_add_i32 s0, s18, 0x4000
	s_mov_b32 m0, s0
	s_nop 0
	global_load_lds_dwordx4 v[18:19], off
	s_waitcnt vmcnt(3) lgkmcnt(0)
	s_barrier
	ds_read_b128 v[34:37], v206
	ds_read_b128 v[38:41], v206 offset:512
	s_waitcnt vmcnt(3) lgkmcnt(1)
	v_mfma_f32_32x32x16_bf16 v[18:33], v[34:37], v[142:145], v[2:17]
	v_lshlrev_b32_e32 v0, 1, v42
	v_and_b32_e32 v202, 32, v0
	v_lshlrev_b32_e32 v0, 4, v42
	s_lshl_b32 s4, s4, 2
	s_add_i32 s17, s4, 0
	s_or_b32 s4, s9, 0xc0
	v_and_b32_e32 v0, 0xc0, v0
	s_waitcnt lgkmcnt(0)
	v_mfma_f32_32x32x16_bf16 v[2:17], v[38:41], v[142:145], v[2:17]
	ds_read_b128 v[34:37], v206 offset:2048
	ds_read_b128 v[38:41], v206 offset:2560
	v_lshl_or_b32 v0, v200, 8, v0
	v_add_u32_e32 v84, 0, v202
	v_mov_b32_e32 v224, 0
	s_movk_i32 s21, 0x4000
	s_mov_b32 s23, -1
	v_writelane_b32 v255, s26, 45
	s_add_i32 s26, s9, 0x100
	s_mov_b32 s0, 0
	s_waitcnt vmcnt(2) lgkmcnt(1)
	v_mfma_f32_32x32x16_bf16 v[18:33], v[34:37], v[138:141], v[18:33]
	s_movk_i32 s24, 0x2000
	v_add3_u32 v207, v84, v201, v0
	v_cmp_gt_u32_e64 s[40:41], 32, v189
	v_lshl_add_u32 v204, v199, 2, s17
	v_lshl_add_u64 v[196:197], v[82:83], 0, s[28:29]
	s_waitcnt lgkmcnt(0)
	v_mfma_f32_32x32x16_bf16 v[2:17], v[38:41], v[138:141], v[2:17]
	ds_read_b128 v[34:37], v206 offset:4096
	ds_read_b128 v[38:41], v206 offset:4608
	s_waitcnt vmcnt(1) lgkmcnt(1)
	v_mfma_f32_32x32x16_bf16 v[18:33], v[34:37], v[130:133], v[18:33]
	s_waitcnt lgkmcnt(0)
	v_mfma_f32_32x32x16_bf16 v[2:17], v[38:41], v[130:133], v[2:17]
	ds_read_b128 v[34:37], v206 offset:6144
	ds_read_b128 v[38:41], v206 offset:6656
	s_waitcnt vmcnt(0) lgkmcnt(1)
	v_mfma_f32_32x32x16_bf16 v[18:33], v[34:37], v[122:125], v[18:33]
	s_waitcnt lgkmcnt(0)
	v_mfma_f32_32x32x16_bf16 v[2:17], v[38:41], v[122:125], v[2:17]
	s_nop 15
	s_nop 7
	s_nop 0
	v_max3_f32 v34, v18, v19, v2
	v_max3_f32 v35, v20, v21, v3
	s_nop 0
	v_max3_f32 v34, v34, v4, v5
	v_max3_f32 v35, v35, v24, v25
	s_nop 0
	v_max3_f32 v34, v34, v22, v23
	v_max3_f32 v35, v35, v8, v9
	s_nop 0
	v_max3_f32 v34, v34, v6, v7
	v_max3_f32 v35, v35, v28, v29
	s_nop 0
	v_max3_f32 v34, v34, v26, v27
	v_max3_f32 v35, v35, v12, v13
	s_nop 0
	v_max3_f32 v34, v34, v10, v11
	v_max3_f32 v35, v35, v32, v33
	s_nop 0
	v_max3_f32 v34, v34, v30, v31
	v_max3_f32 v35, v35, v16, v17
	s_nop 0
	v_max3_f32 v34, v34, v14, v15
	s_nop 0
	v_max_f32_e32 v34, v34, v35
	s_nop 0
	v_mov_b32_e32 v35, v34
	s_nop 1
	v_permlane32_swap_b32_e32 v34, v35
	v_max_f32_e32 v34, v34, v35
	s_nop 0
	v_add_f32_e32 v205, v1, v34
	v_sub_f32_e32 v18, v18, v34
	v_sub_f32_e32 v2, v2, v34
	v_sub_f32_e32 v19, v19, v34
	v_sub_f32_e32 v3, v3, v34
	v_sub_f32_e32 v20, v20, v34
	v_sub_f32_e32 v4, v4, v34
	v_sub_f32_e32 v21, v21, v34
	v_sub_f32_e32 v5, v5, v34
	v_sub_f32_e32 v22, v22, v34
	v_sub_f32_e32 v6, v6, v34
	v_sub_f32_e32 v23, v23, v34
	v_sub_f32_e32 v7, v7, v34
	v_sub_f32_e32 v24, v24, v34
	v_sub_f32_e32 v8, v8, v34
	v_sub_f32_e32 v25, v25, v34
	v_sub_f32_e32 v9, v9, v34
	v_sub_f32_e32 v26, v26, v34
	v_sub_f32_e32 v10, v10, v34
	v_sub_f32_e32 v27, v27, v34
	v_sub_f32_e32 v11, v11, v34
	v_sub_f32_e32 v28, v28, v34
	v_sub_f32_e32 v12, v12, v34
	v_sub_f32_e32 v29, v29, v34
	v_sub_f32_e32 v13, v13, v34
	v_sub_f32_e32 v30, v30, v34
	v_sub_f32_e32 v14, v14, v34
	v_sub_f32_e32 v31, v31, v34
	v_sub_f32_e32 v15, v15, v34
	v_sub_f32_e32 v32, v32, v34
	v_sub_f32_e32 v16, v16, v34
	v_sub_f32_e32 v33, v33, v34
	v_sub_f32_e32 v17, v17, v34
	s_nop 0
	v_xor_b32_e32 v34, 0x80000000, v205
	v_mov_b32_e32 v35, v34
	v_mov_b32_e32 v36, v34
	v_mov_b32_e32 v37, v34
	v_mov_b32_e32 v38, v34
	v_mov_b32_e32 v39, v34
	v_mov_b32_e32 v40, v34
	v_mov_b32_e32 v41, v34
	v_mov_b32_e32 v42, v34
	v_mov_b32_e32 v43, v34
	v_mov_b32_e32 v44, v34
	v_mov_b32_e32 v45, v34
	v_mov_b32_e32 v46, v34
	v_mov_b32_e32 v47, v34
	v_mov_b32_e32 v48, v34
	v_mov_b32_e32 v49, v34
	s_waitcnt vmcnt(0) lgkmcnt(0)
	s_barrier
	v_exp_f32_e32 v50, v2
	v_exp_f32_e32 v51, v3
	v_mad_i64_i32 v[2:3], s[4:5], s4, v217, v[192:193]
	s_mov_b32 m0, s18
	s_nop 0
	global_load_lds_dwordx4 v[2:3], off
	v_exp_f32_e32 v66, v18
	v_mad_i64_i32 v[2:3], s[4:5], s1, v217, v[194:195]
	s_add_i32 s1, s18, 0x8000
	s_mov_b32 m0, s1
	s_nop 0
	global_load_lds_dwordx4 v[2:3], off
	ds_read_b128 v[174:177], v206 offset:8192
	ds_read_b128 v[170:173], v206 offset:8704
	ds_read_b128 v[166:169], v206 offset:10240
	ds_read_b128 v[162:165], v206 offset:10752
	ds_read_b128 v[158:161], v206 offset:12288
	ds_read_b128 v[154:157], v206 offset:12800
	ds_read_b128 v[150:153], v206 offset:14336
	ds_read_b128 v[146:149], v206 offset:14848
	v_exp_f32_e32 v67, v19
	v_exp_f32_e32 v68, v20
	v_exp_f32_e32 v69, v21
	v_exp_f32_e32 v70, v22
	v_exp_f32_e32 v71, v23
	v_exp_f32_e32 v72, v24
	v_exp_f32_e32 v73, v25
	v_exp_f32_e32 v74, v26
	v_exp_f32_e32 v75, v27
	v_exp_f32_e32 v76, v28
	v_exp_f32_e32 v77, v29
	v_exp_f32_e32 v78, v30
	v_exp_f32_e32 v79, v31
	v_exp_f32_e32 v80, v32
	v_exp_f32_e32 v81, v33
	v_exp_f32_e32 v52, v4
	v_exp_f32_e32 v53, v5
	v_exp_f32_e32 v54, v6
	v_exp_f32_e32 v55, v7
	v_exp_f32_e32 v56, v8
	v_exp_f32_e32 v57, v9
	v_exp_f32_e32 v58, v10
	v_exp_f32_e32 v59, v11
	v_exp_f32_e32 v60, v12
	v_exp_f32_e32 v61, v13
	v_exp_f32_e32 v62, v14
	v_exp_f32_e32 v63, v15
	v_exp_f32_e32 v64, v16
	v_exp_f32_e32 v65, v17
	s_waitcnt vmcnt(2) lgkmcnt(0)
	s_barrier
	v_mov_b32_e32 v2, 0
	v_mov_b32_e32 v3, v224
	v_mov_b32_e32 v4, v224
	v_mov_b32_e32 v5, v224
	v_mov_b32_e32 v6, v224
	v_mov_b32_e32 v7, v224
	v_mov_b32_e32 v8, v224
	v_mov_b32_e32 v9, v224
	v_mov_b32_e32 v10, v224
	v_mov_b32_e32 v11, v224
	v_mov_b32_e32 v12, v224
	v_mov_b32_e32 v13, v224
	v_mov_b32_e32 v14, v224
	v_mov_b32_e32 v15, v224
	v_mov_b32_e32 v16, v224
	v_mov_b32_e32 v17, v224
	v_mov_b32_e32 v18, 0
	v_mov_b32_e32 v19, v224
	v_mov_b32_e32 v20, v224
	v_mov_b32_e32 v21, v224
	v_mov_b32_e32 v22, v224
	v_mov_b32_e32 v23, v224
	v_mov_b32_e32 v24, v224
	v_mov_b32_e32 v25, v224
	v_mov_b32_e32 v26, v224
	v_mov_b32_e32 v27, v224
	v_mov_b32_e32 v28, v224
	v_mov_b32_e32 v29, v224
	v_mov_b32_e32 v30, v224
	v_mov_b32_e32 v31, v224
	v_mov_b32_e32 v32, v224
	v_mov_b32_e32 v33, v224
.LBB0_707:
	s_add_i32 s22, s23, 2
	v_add_u32_e32 v186, s0, v207
	ds_read_b64_tr_b16 v[178:179], v186 offset:24576
	ds_read_b64_tr_b16 v[180:181], v186 offset:25088
	s_waitcnt lgkmcnt(9)
	v_mfma_f32_32x32x16_bf16 v[98:113], v[174:177], v[142:145], v[34:49]
	v_add_f32_e32 v82, v66, v67
	v_add_f32_e32 v82, v68, v82
	v_add_f32_e32 v82, v69, v82
	v_add_f32_e32 v82, v70, v82
	v_add_f32_e32 v82, v71, v82
	v_cvt_pk_bf16_f32 v134, v66, v67
	v_cvt_pk_bf16_f32 v135, v68, v69
	ds_read_b64_tr_b16 v[174:175], v186 offset:28672
	ds_read_b64_tr_b16 v[176:177], v186 offset:29184
	v_add_f32_e32 v66, v72, v82
	s_waitcnt lgkmcnt(10)
	v_mfma_f32_32x32x16_bf16 v[82:97], v[170:173], v[142:145], v[34:49]
	v_add_f32_e32 v66, v73, v66
	v_add_f32_e32 v66, v74, v66
	v_add_f32_e32 v114, v75, v66
	v_cvt_pk_bf16_f32 v136, v70, v71
	v_cvt_pk_bf16_f32 v137, v72, v73
	ds_read_b64_tr_b16 v[66:67], v186 offset:25600
	ds_read_b64_tr_b16 v[68:69], v186 offset:26112
	s_waitcnt lgkmcnt(11)
	v_mfma_f32_32x32x16_bf16 v[98:113], v[166:169], v[138:141], v[98:113]
	v_add_f32_e32 v70, v76, v114
	v_add_f32_e32 v70, v77, v70
	v_add_f32_e32 v70, v78, v70
	v_add_f32_e32 v114, v79, v70
	v_cvt_pk_bf16_f32 v126, v74, v75
	v_cvt_pk_bf16_f32 v127, v76, v77
	ds_read_b64_tr_b16 v[70:71], v186 offset:29696
	ds_read_b64_tr_b16 v[72:73], v186 offset:30208
	s_waitcnt lgkmcnt(12)
	v_mfma_f32_32x32x16_bf16 v[82:97], v[162:165], v[138:141], v[82:97]
	v_add_f32_e32 v74, v80, v114
	v_add_f32_e32 v74, v81, v74
	v_add_f32_e32 v74, v50, v74
	v_add_f32_e32 v114, v51, v74
	v_cvt_pk_bf16_f32 v128, v78, v79
	v_cvt_pk_bf16_f32 v129, v80, v81
	ds_read_b64_tr_b16 v[74:75], v186 offset:26624
	ds_read_b64_tr_b16 v[76:77], v186 offset:27136
	s_waitcnt lgkmcnt(13)
	v_mfma_f32_32x32x16_bf16 v[98:113], v[158:161], v[130:133], v[98:113]
	v_add_f32_e32 v78, v52, v114
	v_add_f32_e32 v78, v53, v78
	v_add_f32_e32 v78, v54, v78
	v_add_f32_e32 v78, v55, v78
	v_cvt_pk_bf16_f32 v118, v50, v51
	v_cvt_pk_bf16_f32 v119, v52, v53
	ds_read_b64_tr_b16 v[50:51], v186 offset:30720
	ds_read_b64_tr_b16 v[52:53], v186 offset:31232
	s_waitcnt lgkmcnt(14)
	v_mfma_f32_32x32x16_bf16 v[82:97], v[154:157], v[130:133], v[82:97]
	v_add_f32_e32 v78, v56, v78
	v_add_f32_e32 v78, v57, v78
	v_add_f32_e32 v78, v58, v78
	v_add_f32_e32 v78, v59, v78
	v_cvt_pk_bf16_f32 v120, v54, v55
	v_cvt_pk_bf16_f32 v121, v56, v57
	ds_read_b64_tr_b16 v[54:55], v186 offset:27648
	ds_read_b64_tr_b16 v[56:57], v186 offset:28160
	s_waitcnt lgkmcnt(14)
	v_mfma_f32_32x32x16_bf16 v[98:113], v[150:153], v[122:125], v[98:113]
	v_add_f32_e32 v78, v60, v78
	v_add_f32_e32 v78, v61, v78
	v_add_f32_e32 v78, v62, v78
	v_add_f32_e32 v78, v63, v78
	v_cvt_pk_bf16_f32 v114, v58, v59
	v_cvt_pk_bf16_f32 v115, v60, v61
	ds_read_b64_tr_b16 v[58:59], v186 offset:31744
	ds_read_b64_tr_b16 v[60:61], v186 offset:32256
	v_mfma_f32_32x32x16_bf16 v[82:97], v[146:149], v[122:125], v[82:97]
	v_add_f32_e32 v78, v64, v78
	v_add_f32_e32 v78, v65, v78
	v_cvt_pk_bf16_f32 v116, v62, v63
	v_cvt_pk_bf16_f32 v117, v64, v65
	s_cmpk_gt_u32 s22, 0x7c
	s_cselect_b64 s[0:1], -1, 0
	s_add_i32 m0, s24, s18
	v_mad_i64_i32 v[62:63], s[4:5], s26, v217, v[192:193]
	global_load_lds_dwordx4 v[62:63], off
	s_add_i32 s26, s26, 64
	v_max_f32_e32 v62, v98, v99
	v_max3_f32 v63, v100, v101, v83
	v_max3_f32 v62, v62, v82, v84
	v_max3_f32 v62, v62, v85, v102
	v_max3_f32 v63, v63, v104, v105
	v_max3_f32 v62, v62, v103, v86
	v_max3_f32 v63, v63, v88, v89
	v_max3_f32 v62, v62, v87, v106
	v_max3_f32 v63, v63, v108, v109
	v_max3_f32 v62, v62, v107, v90
	v_max3_f32 v63, v63, v92, v93
	v_max3_f32 v62, v62, v91, v110
	v_max3_f32 v63, v63, v112, v113
	v_max3_f32 v62, v62, v111, v94
	v_max3_f32 v63, v63, v96, v97
	v_max3_f32 v62, v62, v95, v63
	v_mov_b32_e32 v63, v62
	s_add_i32 m0, s21, s19
	s_nop 0
	v_permlane32_swap_b32_e32 v62, v63
	global_load_lds_dwordx4 v[196:197], off
	v_max_f32_e32 v62, v62, v63
	v_cmp_lt_f32_e32 vcc, s51, v62
	s_cmp_lg_u64 vcc, 0
	v_add_f32_e32 v224, v224, v78
	s_cselect_b64 s[4:5], -1, 0
	s_cbranch_vccnz .LBB0_715

.LBB0_710:
	s_add_i32 s4, s21, 0x2000
	s_cmpk_lg_i32 s21, 0x4000
	s_cselect_b32 s25, s4, 0
	v_add_u32_e32 v186, s24, v207
	ds_read_b64_tr_b16 v[150:151], v186 offset:24576
	ds_read_b64_tr_b16 v[152:153], v186 offset:25088
	s_waitcnt lgkmcnt(9)
	v_mfma_f32_32x32x16_bf16 v[66:81], v[62:65], v[142:145], v[34:49]
	v_add_f32_e32 v50, v98, v99
	v_add_f32_e32 v50, v100, v50
	v_add_f32_e32 v50, v101, v50
	v_add_f32_e32 v50, v102, v50
	v_add_f32_e32 v50, v103, v50
	v_cvt_pk_bf16_f32 v134, v98, v99
	v_cvt_pk_bf16_f32 v135, v100, v101
	ds_read_b64_tr_b16 v[146:147], v186 offset:28672
	ds_read_b64_tr_b16 v[148:149], v186 offset:29184
	v_add_f32_e32 v50, v104, v50
	v_add_f32_e32 v50, v105, v50
	v_add_f32_e32 v50, v106, v50
	v_add_f32_e32 v114, v107, v50
	s_waitcnt lgkmcnt(10)
	v_mfma_f32_32x32x16_bf16 v[50:65], v[174:177], v[142:145], v[34:49]
	v_cvt_pk_bf16_f32 v136, v102, v103
	v_cvt_pk_bf16_f32 v137, v104, v105
	ds_read_b64_tr_b16 v[98:99], v186 offset:25600
	ds_read_b64_tr_b16 v[100:101], v186 offset:26112
	s_waitcnt lgkmcnt(11)
	v_mfma_f32_32x32x16_bf16 v[66:81], v[178:181], v[138:141], v[66:81]
	v_add_f32_e32 v102, v108, v114
	v_add_f32_e32 v102, v109, v102
	v_add_f32_e32 v102, v110, v102
	v_add_f32_e32 v114, v111, v102
	v_cvt_pk_bf16_f32 v126, v106, v107
	v_cvt_pk_bf16_f32 v127, v108, v109
	ds_read_b64_tr_b16 v[102:103], v186 offset:29696
	ds_read_b64_tr_b16 v[104:105], v186 offset:30208
	s_waitcnt lgkmcnt(12)
	v_mfma_f32_32x32x16_bf16 v[50:65], v[170:173], v[138:141], v[50:65]
	v_add_f32_e32 v106, v112, v114
	v_add_f32_e32 v106, v113, v106
	v_add_f32_e32 v106, v82, v106
	v_add_f32_e32 v114, v83, v106
	v_cvt_pk_bf16_f32 v128, v110, v111
	v_cvt_pk_bf16_f32 v129, v112, v113
	ds_read_b64_tr_b16 v[106:107], v186 offset:26624
	ds_read_b64_tr_b16 v[108:109], v186 offset:27136
	s_waitcnt lgkmcnt(13)
	v_mfma_f32_32x32x16_bf16 v[66:81], v[166:169], v[130:133], v[66:81]
	v_add_f32_e32 v110, v84, v114
	v_add_f32_e32 v110, v85, v110
	v_add_f32_e32 v110, v86, v110
	v_add_f32_e32 v110, v87, v110
	v_cvt_pk_bf16_f32 v118, v82, v83
	v_cvt_pk_bf16_f32 v119, v84, v85
	ds_read_b64_tr_b16 v[82:83], v186 offset:30720
	ds_read_b64_tr_b16 v[84:85], v186 offset:31232
	s_waitcnt lgkmcnt(14)
	v_mfma_f32_32x32x16_bf16 v[50:65], v[162:165], v[130:133], v[50:65]
	v_add_f32_e32 v110, v88, v110
	v_add_f32_e32 v110, v89, v110
	v_add_f32_e32 v110, v90, v110
	v_add_f32_e32 v110, v91, v110
	v_cvt_pk_bf16_f32 v120, v86, v87
	v_cvt_pk_bf16_f32 v121, v88, v89
	ds_read_b64_tr_b16 v[86:87], v186 offset:27648
	ds_read_b64_tr_b16 v[88:89], v186 offset:28160
	s_waitcnt lgkmcnt(14)
	v_mfma_f32_32x32x16_bf16 v[66:81], v[158:161], v[122:125], v[66:81]
	v_add_f32_e32 v110, v92, v110
	v_add_f32_e32 v110, v93, v110
	v_add_f32_e32 v110, v94, v110
	v_add_f32_e32 v110, v95, v110
	v_cvt_pk_bf16_f32 v114, v90, v91
	v_cvt_pk_bf16_f32 v115, v92, v93
	ds_read_b64_tr_b16 v[90:91], v186 offset:31744
	ds_read_b64_tr_b16 v[92:93], v186 offset:32256
	v_mfma_f32_32x32x16_bf16 v[50:65], v[154:157], v[122:125], v[50:65]
	v_add_f32_e32 v110, v96, v110
	v_add_f32_e32 v110, v97, v110
	v_cvt_pk_bf16_f32 v116, v94, v95
	v_cvt_pk_bf16_f32 v117, v96, v97
	s_add_i32 m0, s21, s18
	v_mad_i64_i32 v[94:95], s[4:5], s26, v217, v[192:193]
	global_load_lds_dwordx4 v[94:95], off
	s_add_i32 s26, s26, 64
	s_cmp_eq_u32 s22, 0x7b
	s_cselect_b32 s26, s20, s26
	v_lshl_add_u64 v[94:95], v[196:197], 0, s[30:31]
	s_add_i32 s4, s25, s19
	s_mov_b32 m0, s4
	s_nop 0
	global_load_lds_dwordx4 v[94:95], off
	v_max_f32_e32 v94, v66, v67
	v_max3_f32 v95, v68, v69, v51
	v_max3_f32 v94, v94, v50, v52
	v_max3_f32 v94, v94, v53, v70
	v_max3_f32 v95, v95, v72, v73
	v_max3_f32 v94, v94, v71, v54
	v_max3_f32 v95, v95, v56, v57
	v_max3_f32 v94, v94, v55, v74
	v_max3_f32 v95, v95, v76, v77
	v_max3_f32 v94, v94, v75, v58
	v_max3_f32 v95, v95, v60, v61
	v_max3_f32 v94, v94, v59, v78
	v_max3_f32 v95, v95, v80, v81
	v_max3_f32 v94, v94, v79, v62
	v_max3_f32 v95, v95, v64, v65
	v_max3_f32 v94, v94, v63, v95
	v_mov_b32_e32 v95, v94
	s_nop 1
	v_permlane32_swap_b32_e32 v94, v95
	v_max_f32_e32 v94, v94, v95
	v_cmp_lt_f32_e32 vcc, s51, v94
	s_cmp_lg_u64 vcc, 0
	v_add_f32_e32 v224, v224, v110
	s_cselect_b64 s[4:5], -1, 0
	s_cbranch_vccnz .LBB0_718

.LBB0_721:
	v_readlane_b32 s26, v255, 45
	v_mad_i64_i32 v[194:195], s[0:1], s20, v217, v[194:195]
	s_add_i32 s20, s8, 0x40c0
	s_movk_i32 s21, 0x7f
	s_movk_i32 s22, 0x4000
	s_movk_i32 s23, 0x2000
	s_mov_b32 s0, 0
